# phase 2 (mla_norm): all of a row's loads issued at the top of the iteration (one memory round trip per row instead of three)
# baseline (speedup 1.0000x reference)
.LBB0_530:
	v_lshl_add_u64 v[44:45], s[70:71], 0, v[16:17]
	global_load_dwordx4 v[28:31], v[44:45], off offset:-2064
	global_load_dwordx4 v[32:35], v[44:45], off offset:-2048
	global_load_dwordx4 v[60:63], v[44:45], off offset:-16
	global_load_dwordx4 v[64:67], v[44:45], off
	global_load_dwordx4 v[68:71], v[8:9], off offset:16
	global_load_dwordx4 v[72:75], v[8:9], off
	s_and_saveexec_b64 s[4:5], s[0:1]
	v_lshl_add_u64 v[80:81], s[70:71], 0, v[18:19]
	v_add_co_u32_e32 v80, vcc, 0x10001000, v80
	v_lshl_add_u64 v[82:83], s[70:71], 0, v[12:13]
	s_nop 0
	v_addc_co_u32_e32 v81, vcc, 0, v81, vcc
	global_load_dword v76, v[80:81], off
	global_load_dword v77, v[80:81], off offset:128
	global_load_dwordx2 v[78:79], v[82:83], off
	s_or_b64 exec, exec, s[4:5]
	v_lshl_add_u64 v[46:47], s[70:71], 0, v[14:15]
	s_waitcnt vmcnt(7)
	v_mul_f32_e32 v42, v29, v29
	v_mul_f32_e32 v43, v31, v31
	v_pk_mul_f32 v[36:37], v[34:35], v[34:35]
	v_pk_mul_f32 v[38:39], v[32:33], v[32:33]
	v_fmac_f32_e32 v42, v28, v28
	v_fmac_f32_e32 v43, v30, v30
	v_mov_b32_e32 v40, v36
	v_mov_b32_e32 v41, v38
	v_mov_b32_e32 v38, v37
	v_add_f32_e32 v42, v42, v43
	v_pk_add_f32 v[36:37], v[40:41], v[38:39]
	s_nop 0
	v_add_f32_e32 v37, v42, v37
	v_add_f32_e32 v36, v36, v37
	ds_bpermute_b32 v37, v20, v36
	s_waitcnt lgkmcnt(0)
	v_add_f32_e32 v36, v36, v37
	ds_bpermute_b32 v37, v21, v36
	s_waitcnt lgkmcnt(0)
	v_add_f32_e32 v36, v36, v37
	ds_bpermute_b32 v37, v22, v36
	s_waitcnt lgkmcnt(0)
	v_add_f32_e32 v36, v36, v37
	ds_bpermute_b32 v37, v23, v36
	s_waitcnt lgkmcnt(0)
	v_add_f32_e32 v36, v36, v37
	ds_bpermute_b32 v37, v24, v36
	s_waitcnt lgkmcnt(0)
	v_add_f32_e32 v36, v36, v37
	ds_bpermute_b32 v37, v25, v36
	s_waitcnt lgkmcnt(0)
	v_add_f32_e32 v36, v36, v37
	v_fmamk_f32 v36, v36, 0x3b000000, v26
	v_mul_f32_e32 v37, 0x4f800000, v36
	v_cmp_gt_f32_e32 vcc, s7, v36
	s_nop 1
	v_cndmask_b32_e32 v36, v36, v37, vcc
	v_sqrt_f32_e32 v37, v36
	s_nop 0
	v_add_u32_e32 v38, -1, v37
	v_add_u32_e32 v39, 1, v37
	v_fma_f32 v40, -v38, v37, v36
	v_fma_f32 v41, -v39, v37, v36
	v_cmp_ge_f32_e64 s[4:5], 0, v40
	s_nop 1
	v_cndmask_b32_e64 v37, v37, v38, s[4:5]
	v_cmp_lt_f32_e64 s[4:5], 0, v41
	s_nop 1
	v_cndmask_b32_e64 v37, v37, v39, s[4:5]
	v_mul_f32_e32 v38, 0x37800000, v37
	v_cndmask_b32_e32 v37, v37, v38, vcc
	v_cmp_class_f32_e32 vcc, v36, v27
	s_nop 1
	v_cndmask_b32_e32 v38, v37, v36, vcc
	v_div_scale_f32 v39, s[4:5], v38, v38, 1.0
	v_rcp_f32_e32 v40, v39
	v_add_co_u32_e32 v36, vcc, s9, v46
	v_fma_f32 v42, -v39, v40, 1.0
	s_nop 0
	v_addc_co_u32_e32 v37, vcc, 0, v47, vcc
	v_div_scale_f32 v41, vcc, 1.0, v38, 1.0
	v_fmac_f32_e32 v40, v42, v40
	v_mul_f32_e32 v42, v41, v40
	v_fma_f32 v43, -v39, v42, v41
	v_fmac_f32_e32 v42, v43, v40
	v_fma_f32 v39, -v39, v42, v41
	v_div_fmas_f32 v39, v39, v40, v42
	v_div_fixup_f32 v38, v39, v38, 1.0
	v_pk_mul_f32 v[28:29], v[28:29], v[38:39] op_sel_hi:[1,0]
	v_pk_mul_f32 v[30:31], v[30:31], v[38:39] op_sel_hi:[1,0]
	v_pk_mul_f32 v[32:33], v[32:33], v[38:39] op_sel_hi:[1,0]
	v_pk_mul_f32 v[34:35], v[34:35], v[38:39] op_sel_hi:[1,0]
	v_pk_mul_f32 v[30:31], v[6:7], v[30:31]
	v_pk_mul_f32 v[28:29], v[4:5], v[28:29]
	v_pk_mul_f32 v[34:35], v[2:3], v[34:35]
	v_pk_mul_f32 v[32:33], v[0:1], v[32:33]
	v_cvt_pk_bf16_f32 v28, v28, v29
	v_cvt_pk_bf16_f32 v29, v30, v31
	s_nop 0
	v_cvt_pk_bf16_f32 v30, v32, v33
	v_cvt_pk_bf16_f32 v31, v34, v35
	global_store_dwordx4 v[36:37], v[28:31], off
	s_waitcnt vmcnt(7)
	v_mul_f32_e32 v52, v61, v61
	v_mul_f32_e32 v53, v63, v63
	s_waitcnt vmcnt(6)
	v_pk_mul_f32 v[44:45], v[66:67], v[66:67]
	v_pk_mul_f32 v[48:49], v[64:65], v[64:65]
	v_fmac_f32_e32 v52, v60, v60
	v_fmac_f32_e32 v53, v62, v62
	v_mov_b32_e32 v50, v44
	v_mov_b32_e32 v51, v48
	v_mov_b32_e32 v48, v45
	v_add_f32_e32 v52, v52, v53
	v_pk_add_f32 v[44:45], v[50:51], v[48:49]
	s_nop 0
	v_add_f32_e32 v45, v52, v45
	v_add_f32_e32 v44, v44, v45
	ds_bpermute_b32 v45, v20, v44
	s_waitcnt lgkmcnt(0)
	v_add_f32_e32 v44, v44, v45
	ds_bpermute_b32 v45, v21, v44
	s_waitcnt lgkmcnt(0)
	v_add_f32_e32 v44, v44, v45
	ds_bpermute_b32 v45, v22, v44
	s_waitcnt lgkmcnt(0)
	v_add_f32_e32 v44, v44, v45
	ds_bpermute_b32 v45, v23, v44
	s_waitcnt lgkmcnt(0)
	v_add_f32_e32 v44, v44, v45
	ds_bpermute_b32 v45, v24, v44
	s_waitcnt lgkmcnt(0)
	v_add_f32_e32 v44, v44, v45
	ds_bpermute_b32 v45, v25, v44
	s_waitcnt lgkmcnt(0)
	v_add_f32_e32 v44, v44, v45
	v_fmamk_f32 v44, v44, 0x3b000000, v26
	v_mul_f32_e32 v45, 0x4f800000, v44
	v_cmp_gt_f32_e32 vcc, s7, v44
	s_nop 1
	v_cndmask_b32_e32 v44, v44, v45, vcc
	v_sqrt_f32_e32 v45, v44
	s_nop 0
	v_add_u32_e32 v48, -1, v45
	v_add_u32_e32 v49, 1, v45
	v_fma_f32 v50, -v48, v45, v44
	v_fma_f32 v51, -v49, v45, v44
	v_cmp_ge_f32_e64 s[4:5], 0, v50
	s_nop 1
	v_cndmask_b32_e64 v45, v45, v48, s[4:5]
	v_cmp_lt_f32_e64 s[4:5], 0, v51
	s_nop 1
	v_cndmask_b32_e64 v45, v45, v49, s[4:5]
	v_mul_f32_e32 v48, 0x37800000, v45
	v_cndmask_b32_e32 v45, v45, v48, vcc
	v_cmp_class_f32_e32 vcc, v44, v27
	s_nop 1
	v_cndmask_b32_e32 v45, v45, v44, vcc
	v_div_scale_f32 v44, s[4:5], v45, v45, 1.0
	v_rcp_f32_e32 v48, v44
	v_div_scale_f32 v49, vcc, 1.0, v45, 1.0
	v_fma_f32 v50, -v44, v48, 1.0
	v_fmac_f32_e32 v48, v50, v48
	v_mul_f32_e32 v50, v49, v48
	v_fma_f32 v51, -v44, v50, v49
	v_fmac_f32_e32 v50, v51, v48
	v_fma_f32 v44, -v44, v50, v49
	v_div_fmas_f32 v48, v44, v48, v50
	v_add_co_u32_e32 v44, vcc, 0x23000000, v46
	v_div_fixup_f32 v46, v48, v45, 1.0
	v_pk_mul_f32 v[60:61], v[60:61], v[46:47] op_sel_hi:[1,0]
	v_pk_mul_f32 v[62:63], v[62:63], v[46:47] op_sel_hi:[1,0]
	v_pk_mul_f32 v[64:65], v[64:65], v[46:47] op_sel_hi:[1,0]
	v_pk_mul_f32 v[66:67], v[66:67], v[46:47] op_sel_hi:[1,0]
	s_waitcnt vmcnt(4)
	v_pk_mul_f32 v[62:63], v[74:75], v[62:63]
	v_pk_mul_f32 v[60:61], v[72:73], v[60:61]
	v_addc_co_u32_e32 v45, vcc, 0, v47, vcc
	v_pk_mul_f32 v[66:67], v[70:71], v[66:67]
	v_pk_mul_f32 v[64:65], v[68:69], v[64:65]
	v_cvt_pk_bf16_f32 v60, v60, v61
	v_cvt_pk_bf16_f32 v61, v62, v63
	s_nop 0
	v_cvt_pk_bf16_f32 v62, v64, v65
	v_cvt_pk_bf16_f32 v63, v66, v67
	global_store_dwordx4 v[44:45], v[60:63], off
	s_and_saveexec_b64 s[4:5], s[0:1]
	s_cbranch_execz .LBB0_529
	s_waitcnt vmcnt(4)
	v_mov_b32_e32 v31, v76
	s_waitcnt vmcnt(3)
	v_mov_b32_e32 v30, v77
	s_waitcnt vmcnt(2)
	v_pk_mul_f32 v[28:29], v[76:77], v[78:79]
	s_nop 0
	v_sub_f32_e32 v76, v28, v29
	v_pk_mul_f32 v[28:29], v[30:31], v[78:79]
	s_nop 0
	v_add_f32_e32 v28, v28, v29
	v_cvt_pk_bf16_f32 v30, v76, v28
	v_lshl_add_u64 v[28:29], s[70:71], 0, v[10:11]
	global_store_dword v[28:29], v30, off
	s_branch .LBB0_529
